# pool waiting-mode converts with 5 waves per round instead of 3 (on E1+E2+E6)
# speedup vs baseline: 1.0142x; 1.0013x over previous
.LBB0_70:
	v_mov_b32_e32 v2, s72
	ds_read_b32 v2, v2
	s_mov_b32 s2, 0x3307f
	s_waitcnt lgkmcnt(0)
	v_cmp_lt_u32_e32 vcc, s2, v2
	v_mov_b32_e32 v2, -1
	s_cbranch_vccnz .LBB0_76
	global_load_dword v4, v67, s[66:67] sc1
	v_add_u32_e32 v3, -1, v3
	v_mov_b32_e32 v2, -1
	s_waitcnt vmcnt(0)
	v_cmp_eq_u32_e32 vcc, v4, v3
	s_and_saveexec_b64 s[26:27], vcc
	s_cbranch_execz .LBB0_75
	s_mov_b64 s[28:29], exec
	v_mbcnt_lo_u32_b32 v2, s28, 0
	v_mbcnt_hi_u32_b32 v2, s29, v2
	v_cmp_eq_u32_e32 vcc, 0, v2
	s_and_saveexec_b64 s[6:7], vcc
	s_cbranch_execz .LBB0_74
	s_bcnt1_i32_b64 s2, s[28:29]
	s_mul_i32 s2, s2, 5
	v_mov_b32_e32 v3, s2
	global_atomic_add v3, v67, v3, s[24:25] sc0
.LBB0_74:
	s_or_b64 exec, exec, s[6:7]
	s_waitcnt vmcnt(0)
	v_readfirstlane_b32 s2, v3
	v_mov_b32_e32 v4, s72
	s_nop 0
	v_mad_u32_u24 v2, v2, 5, s2
	v_add_u32_e32 v3, 5, v2
	ds_write_b32 v4, v3
	v_mov_b32_e32 v3, s33
	v_mov_b32_e32 v4, 5
	ds_write_b32 v3, v4

.LBB0_365:
	v_readlane_b32 s2, v252, 24
	s_nop 1
	v_mov_b32_e32 v2, s2
	ds_read_b32 v2, v2
	s_mov_b32 s2, 0x3307f
	s_waitcnt lgkmcnt(0)
	v_cmp_lt_u32_e32 vcc, s2, v2
	v_mov_b32_e32 v2, -1
	s_cbranch_vccnz .LBB0_371
	v_readlane_b32 s12, v252, 34
	v_readlane_b32 s13, v252, 35
	v_add_u32_e32 v3, -1, v3
	v_mov_b32_e32 v2, -1
	s_nop 2
	global_load_dword v4, v147, s[12:13] sc1
	s_waitcnt vmcnt(0)
	v_cmp_eq_u32_e32 vcc, v4, v3
	s_and_saveexec_b64 s[18:19], vcc
	s_cbranch_execz .LBB0_370
	s_mov_b64 s[36:37], exec
	v_mbcnt_lo_u32_b32 v2, s36, 0
	v_mbcnt_hi_u32_b32 v2, s37, v2
	v_cmp_eq_u32_e32 vcc, 0, v2
	s_and_saveexec_b64 s[30:31], vcc
	s_cbranch_execz .LBB0_369
	s_bcnt1_i32_b64 s2, s[36:37]
	s_mul_i32 s2, s2, 5
	v_mov_b32_e32 v3, s2
	global_atomic_add v3, v147, v3, s[34:35] sc0
.LBB0_369:
	s_or_b64 exec, exec, s[30:31]
	s_waitcnt vmcnt(0)
	v_readfirstlane_b32 s2, v3
	s_nop 1
	v_mad_u32_u24 v2, v2, 5, s2
	v_readlane_b32 s2, v252, 24
	v_add_u32_e32 v3, 5, v2
	s_nop 0
	v_mov_b32_e32 v4, s2
	v_readlane_b32 s2, v252, 22
	ds_write_b32 v4, v3
	s_nop 0
	v_mov_b32_e32 v3, s2
	v_mov_b32_e32 v4, 5
	ds_write_b32 v3, v4
